# non-temporal hint on the UP epilogue's hid stores (268 MB/layer streamed once) so they stop evicting x and ACT2 from the Infinity Cache
# speedup vs baseline: 1.1490x; 1.0100x over previous
.Lgm0_loop:
	v_mfma_f32_16x16x32_bf16 v[128:131], v[212:215], v[186:189], v[128:131]
	v_mfma_f32_16x16x32_bf16 v[96:99], v[212:215], v[190:193], v[96:99]
	v_mfma_f32_16x16x32_bf16 v[108:111], v[212:215], v[194:197], v[108:111]
	v_mfma_f32_16x16x32_bf16 v[132:135], v[212:215], v[208:211], v[132:135]
	v_mfma_f32_16x16x32_bf16 v[116:119], v[216:219], v[186:189], v[116:119]
	v_mfma_f32_16x16x32_bf16 v[92:95], v[216:219], v[190:193], v[92:95]
	v_mfma_f32_16x16x32_bf16 v[112:115], v[216:219], v[194:197], v[112:115]
	v_mfma_f32_16x16x32_bf16 v[136:139], v[216:219], v[208:211], v[136:139]
	v_mfma_f32_16x16x32_bf16 v[104:107], v[220:223], v[186:189], v[104:107]
	v_mfma_f32_16x16x32_bf16 v[88:91], v[220:223], v[190:193], v[88:91]
	v_mfma_f32_16x16x32_bf16 v[120:123], v[220:223], v[194:197], v[120:123]
	v_mfma_f32_16x16x32_bf16 v[140:143], v[220:223], v[208:211], v[140:143]
	v_mfma_f32_16x16x32_bf16 v[100:103], v[224:227], v[186:189], v[100:103]
	v_mfma_f32_16x16x32_bf16 v[84:87], v[224:227], v[190:193], v[84:87]
	v_mfma_f32_16x16x32_bf16 v[124:127], v[224:227], v[194:197], v[124:127]
	v_mfma_f32_16x16x32_bf16 v[144:147], v[224:227], v[208:211], v[144:147]
	s_waitcnt vmcnt(6)
	s_barrier
	v_add_u32_e32 v248, s30, v155
	v_add_u32_e32 v249, s30, v160
	v_mfma_f32_16x16x32_bf16 v[52:55], v[228:231], v[186:189], v[52:55]
	ds_read_b128 v[0:3], v248
	s_add_u32 m0, s25, s24
	v_mfma_f32_16x16x32_bf16 v[36:39], v[228:231], v[190:193], v[36:39]
	ds_read_b128 v[16:19], v249 offset:8192
	global_load_lds_dwordx4 v156, s[26:27]
	v_mfma_f32_16x16x32_bf16 v[64:67], v[228:231], v[194:197], v[64:67]
	ds_read_b128 v[4:7], v248 offset:1024
	s_add_u32 m0, m0, 0x1000
	v_mfma_f32_16x16x32_bf16 v[76:79], v[228:231], v[208:211], v[76:79]
	ds_read_b128 v[20:23], v249 offset:9216
	global_load_lds_dwordx4 v157, s[26:27]
	v_mfma_f32_16x16x32_bf16 v[48:51], v[232:235], v[186:189], v[48:51]
	ds_read_b128 v[8:11], v248 offset:2048
	s_add_u32 m0, m0, 0x1000
	v_mfma_f32_16x16x32_bf16 v[32:35], v[232:235], v[190:193], v[32:35]
	ds_read_b128 v[162:165], v249 offset:10240
	global_load_lds_dwordx4 v156, s[28:29]
	v_mfma_f32_16x16x32_bf16 v[68:71], v[232:235], v[194:197], v[68:71]
	ds_read_b128 v[12:15], v248 offset:3072
	s_add_u32 m0, m0, 0x1000
	v_mfma_f32_16x16x32_bf16 v[72:75], v[232:235], v[208:211], v[72:75]
	ds_read_b128 v[166:169], v249 offset:11264
	global_load_lds_dwordx4 v157, s[28:29]
	v_mfma_f32_16x16x32_bf16 v[44:47], v[236:239], v[186:189], v[44:47]
	ds_read_b128 v[170:173], v249 offset:12288
	s_add_u32 m0, m0, 0x1000
	v_mfma_f32_16x16x32_bf16 v[28:31], v[236:239], v[190:193], v[28:31]
	ds_read_b128 v[174:177], v249 offset:13312
	global_load_lds_dwordx4 v158, s[28:29]
	v_mfma_f32_16x16x32_bf16 v[80:83], v[236:239], v[194:197], v[80:83]
	ds_read_b128 v[178:181], v249 offset:14336
	s_add_u32 m0, m0, 0x1000
	v_mfma_f32_16x16x32_bf16 v[60:63], v[236:239], v[208:211], v[60:63]
	ds_read_b128 v[182:185], v249 offset:15360
	global_load_lds_dwordx4 v159, s[28:29]
	v_mfma_f32_16x16x32_bf16 v[40:43], v[240:243], v[186:189], v[40:43]
	v_mfma_f32_16x16x32_bf16 v[24:27], v[240:243], v[190:193], v[24:27]
	v_mfma_f32_16x16x32_bf16 v[56:59], v[240:243], v[194:197], v[56:59]
	v_mfma_f32_16x16x32_bf16 v[148:151], v[240:243], v[208:211], v[148:151]
	s_add_u32 s26, s26, 0x200000
	s_addc_u32 s27, s27, 0
	s_add_u32 s28, s28, 0x40000
	s_addc_u32 s29, s29, 0
	s_add_u32 s25, s25, 24576
	s_cmp_eq_u32 s25, 73728
	s_cselect_b32 s25, 0, s25
	s_add_u32 s30, s30, 24576
	s_cmp_eq_u32 s30, 73728
	s_cselect_b32 s30, 0, s30
	s_waitcnt lgkmcnt(0)
	v_mfma_f32_16x16x32_bf16 v[128:131], v[16:19], v[0:3], v[128:131]
	v_mfma_f32_16x16x32_bf16 v[96:99], v[16:19], v[4:7], v[96:99]
	v_mfma_f32_16x16x32_bf16 v[108:111], v[16:19], v[8:11], v[108:111]
	v_mfma_f32_16x16x32_bf16 v[132:135], v[16:19], v[12:15], v[132:135]
	v_mfma_f32_16x16x32_bf16 v[116:119], v[20:23], v[0:3], v[116:119]
	v_mfma_f32_16x16x32_bf16 v[92:95], v[20:23], v[4:7], v[92:95]
	v_mfma_f32_16x16x32_bf16 v[112:115], v[20:23], v[8:11], v[112:115]
	v_mfma_f32_16x16x32_bf16 v[136:139], v[20:23], v[12:15], v[136:139]
	v_mfma_f32_16x16x32_bf16 v[104:107], v[162:165], v[0:3], v[104:107]
	v_mfma_f32_16x16x32_bf16 v[88:91], v[162:165], v[4:7], v[88:91]
	v_mfma_f32_16x16x32_bf16 v[120:123], v[162:165], v[8:11], v[120:123]
	v_mfma_f32_16x16x32_bf16 v[140:143], v[162:165], v[12:15], v[140:143]
	v_mfma_f32_16x16x32_bf16 v[100:103], v[166:169], v[0:3], v[100:103]
	v_mfma_f32_16x16x32_bf16 v[84:87], v[166:169], v[4:7], v[84:87]
	v_mfma_f32_16x16x32_bf16 v[124:127], v[166:169], v[8:11], v[124:127]
	v_mfma_f32_16x16x32_bf16 v[144:147], v[166:169], v[12:15], v[144:147]
	s_waitcnt vmcnt(6)
	s_barrier
	v_add_u32_e32 v248, s30, v155
	v_add_u32_e32 v249, s30, v160
	v_mfma_f32_16x16x32_bf16 v[52:55], v[170:173], v[0:3], v[52:55]
	ds_read_b128 v[186:189], v248
	s_add_u32 m0, s25, s24
	v_mfma_f32_16x16x32_bf16 v[36:39], v[170:173], v[4:7], v[36:39]
	ds_read_b128 v[212:215], v249 offset:8192
	global_load_lds_dwordx4 v156, s[26:27]
	v_mfma_f32_16x16x32_bf16 v[64:67], v[170:173], v[8:11], v[64:67]
	ds_read_b128 v[190:193], v248 offset:1024
	s_add_u32 m0, m0, 0x1000
	v_mfma_f32_16x16x32_bf16 v[76:79], v[170:173], v[12:15], v[76:79]
	ds_read_b128 v[216:219], v249 offset:9216
	global_load_lds_dwordx4 v157, s[26:27]
	v_mfma_f32_16x16x32_bf16 v[48:51], v[174:177], v[0:3], v[48:51]
	ds_read_b128 v[194:197], v248 offset:2048
	s_add_u32 m0, m0, 0x1000
	v_mfma_f32_16x16x32_bf16 v[32:35], v[174:177], v[4:7], v[32:35]
	ds_read_b128 v[220:223], v249 offset:10240
	global_load_lds_dwordx4 v156, s[28:29]
	v_mfma_f32_16x16x32_bf16 v[68:71], v[174:177], v[8:11], v[68:71]
	ds_read_b128 v[208:211], v248 offset:3072
	s_add_u32 m0, m0, 0x1000
	v_mfma_f32_16x16x32_bf16 v[72:75], v[174:177], v[12:15], v[72:75]
	ds_read_b128 v[224:227], v249 offset:11264
	global_load_lds_dwordx4 v157, s[28:29]
	v_mfma_f32_16x16x32_bf16 v[44:47], v[178:181], v[0:3], v[44:47]
	ds_read_b128 v[228:231], v249 offset:12288
	s_add_u32 m0, m0, 0x1000
	v_mfma_f32_16x16x32_bf16 v[28:31], v[178:181], v[4:7], v[28:31]
	ds_read_b128 v[232:235], v249 offset:13312
	global_load_lds_dwordx4 v158, s[28:29]
	v_mfma_f32_16x16x32_bf16 v[80:83], v[178:181], v[8:11], v[80:83]
	ds_read_b128 v[236:239], v249 offset:14336
	s_add_u32 m0, m0, 0x1000
	v_mfma_f32_16x16x32_bf16 v[60:63], v[178:181], v[12:15], v[60:63]
	ds_read_b128 v[240:243], v249 offset:15360
	global_load_lds_dwordx4 v159, s[28:29]
	v_mfma_f32_16x16x32_bf16 v[40:43], v[182:185], v[0:3], v[40:43]
	v_mfma_f32_16x16x32_bf16 v[24:27], v[182:185], v[4:7], v[24:27]
	v_mfma_f32_16x16x32_bf16 v[56:59], v[182:185], v[8:11], v[56:59]
	v_mfma_f32_16x16x32_bf16 v[148:151], v[182:185], v[12:15], v[148:151]
	s_add_u32 s26, s26, 0x200000
	s_addc_u32 s27, s27, 0
	s_add_u32 s28, s28, 0x40000
	s_addc_u32 s29, s29, 0
	s_add_u32 s25, s25, 24576
	s_cmp_eq_u32 s25, 73728
	s_cselect_b32 s25, 0, s25
	s_add_u32 s30, s30, 24576
	s_cmp_eq_u32 s30, 73728
	s_cselect_b32 s30, 0, s30
	s_waitcnt lgkmcnt(0)
	s_sub_u32 s31, s31, 1
	s_cmp_lg_u32 s31, 0
	s_cbranch_scc1 .Lgm0_loop
	v_mfma_f32_16x16x32_bf16 v[128:131], v[212:215], v[186:189], v[128:131]
	v_mfma_f32_16x16x32_bf16 v[96:99], v[212:215], v[190:193], v[96:99]
	v_mfma_f32_16x16x32_bf16 v[108:111], v[212:215], v[194:197], v[108:111]
	v_mfma_f32_16x16x32_bf16 v[132:135], v[212:215], v[208:211], v[132:135]
	v_mfma_f32_16x16x32_bf16 v[116:119], v[216:219], v[186:189], v[116:119]
	v_mfma_f32_16x16x32_bf16 v[92:95], v[216:219], v[190:193], v[92:95]
	v_mfma_f32_16x16x32_bf16 v[112:115], v[216:219], v[194:197], v[112:115]
	v_mfma_f32_16x16x32_bf16 v[136:139], v[216:219], v[208:211], v[136:139]
	v_mfma_f32_16x16x32_bf16 v[104:107], v[220:223], v[186:189], v[104:107]
	v_mfma_f32_16x16x32_bf16 v[88:91], v[220:223], v[190:193], v[88:91]
	v_mfma_f32_16x16x32_bf16 v[120:123], v[220:223], v[194:197], v[120:123]
	v_mfma_f32_16x16x32_bf16 v[140:143], v[220:223], v[208:211], v[140:143]
	v_mfma_f32_16x16x32_bf16 v[100:103], v[224:227], v[186:189], v[100:103]
	v_mfma_f32_16x16x32_bf16 v[84:87], v[224:227], v[190:193], v[84:87]
	v_mfma_f32_16x16x32_bf16 v[124:127], v[224:227], v[194:197], v[124:127]
	v_mfma_f32_16x16x32_bf16 v[144:147], v[224:227], v[208:211], v[144:147]
	s_waitcnt vmcnt(6)
	s_barrier
	v_add_u32_e32 v248, s30, v155
	v_add_u32_e32 v249, s30, v160
	v_mfma_f32_16x16x32_bf16 v[52:55], v[228:231], v[186:189], v[52:55]
	ds_read_b128 v[0:3], v248
	s_add_u32 m0, s25, s24
	v_mfma_f32_16x16x32_bf16 v[36:39], v[228:231], v[190:193], v[36:39]
	ds_read_b128 v[16:19], v249 offset:8192
	global_load_lds_dwordx4 v156, s[26:27]
	v_mfma_f32_16x16x32_bf16 v[64:67], v[228:231], v[194:197], v[64:67]
	ds_read_b128 v[4:7], v248 offset:1024
	s_add_u32 m0, m0, 0x1000
	v_mfma_f32_16x16x32_bf16 v[76:79], v[228:231], v[208:211], v[76:79]
	ds_read_b128 v[20:23], v249 offset:9216
	global_load_lds_dwordx4 v157, s[26:27]
	v_mfma_f32_16x16x32_bf16 v[48:51], v[232:235], v[186:189], v[48:51]
	ds_read_b128 v[8:11], v248 offset:2048
	s_add_u32 m0, m0, 0x1000
	v_mfma_f32_16x16x32_bf16 v[32:35], v[232:235], v[190:193], v[32:35]
	ds_read_b128 v[162:165], v249 offset:10240
	global_load_lds_dwordx4 v156, s[28:29]
	v_mfma_f32_16x16x32_bf16 v[68:71], v[232:235], v[194:197], v[68:71]
	ds_read_b128 v[12:15], v248 offset:3072
	s_add_u32 m0, m0, 0x1000
	v_mfma_f32_16x16x32_bf16 v[72:75], v[232:235], v[208:211], v[72:75]
	ds_read_b128 v[166:169], v249 offset:11264
	global_load_lds_dwordx4 v157, s[28:29]
	v_mfma_f32_16x16x32_bf16 v[44:47], v[236:239], v[186:189], v[44:47]
	ds_read_b128 v[170:173], v249 offset:12288
	s_add_u32 m0, m0, 0x1000
	v_mfma_f32_16x16x32_bf16 v[28:31], v[236:239], v[190:193], v[28:31]
	ds_read_b128 v[174:177], v249 offset:13312
	global_load_lds_dwordx4 v158, s[28:29]
	v_mfma_f32_16x16x32_bf16 v[80:83], v[236:239], v[194:197], v[80:83]
	ds_read_b128 v[178:181], v249 offset:14336
	s_add_u32 m0, m0, 0x1000
	v_mfma_f32_16x16x32_bf16 v[60:63], v[236:239], v[208:211], v[60:63]
	ds_read_b128 v[182:185], v249 offset:15360
	global_load_lds_dwordx4 v159, s[28:29]
	v_mfma_f32_16x16x32_bf16 v[40:43], v[240:243], v[186:189], v[40:43]
	v_mfma_f32_16x16x32_bf16 v[24:27], v[240:243], v[190:193], v[24:27]
	v_mfma_f32_16x16x32_bf16 v[56:59], v[240:243], v[194:197], v[56:59]
	v_mfma_f32_16x16x32_bf16 v[148:151], v[240:243], v[208:211], v[148:151]
	s_add_u32 s26, s26, 0x200000
	s_addc_u32 s27, s27, 0
	s_add_u32 s28, s28, 0x40000
	s_addc_u32 s29, s29, 0
	s_add_u32 s25, s25, 24576
	s_cmp_eq_u32 s25, 73728
	s_cselect_b32 s25, 0, s25
	s_add_u32 s30, s30, 24576
	s_cmp_eq_u32 s30, 73728
	s_cselect_b32 s30, 0, s30
	s_waitcnt lgkmcnt(0)
	v_mfma_f32_16x16x32_bf16 v[128:131], v[16:19], v[0:3], v[128:131]
	v_mfma_f32_16x16x32_bf16 v[96:99], v[16:19], v[4:7], v[96:99]
	v_mfma_f32_16x16x32_bf16 v[108:111], v[16:19], v[8:11], v[108:111]
	v_mfma_f32_16x16x32_bf16 v[132:135], v[16:19], v[12:15], v[132:135]
	v_mfma_f32_16x16x32_bf16 v[116:119], v[20:23], v[0:3], v[116:119]
	v_mfma_f32_16x16x32_bf16 v[92:95], v[20:23], v[4:7], v[92:95]
	v_mfma_f32_16x16x32_bf16 v[112:115], v[20:23], v[8:11], v[112:115]
	v_mfma_f32_16x16x32_bf16 v[136:139], v[20:23], v[12:15], v[136:139]
	v_mfma_f32_16x16x32_bf16 v[104:107], v[162:165], v[0:3], v[104:107]
	v_mfma_f32_16x16x32_bf16 v[88:91], v[162:165], v[4:7], v[88:91]
	v_mfma_f32_16x16x32_bf16 v[120:123], v[162:165], v[8:11], v[120:123]
	v_mfma_f32_16x16x32_bf16 v[140:143], v[162:165], v[12:15], v[140:143]
	v_mfma_f32_16x16x32_bf16 v[100:103], v[166:169], v[0:3], v[100:103]
	v_mfma_f32_16x16x32_bf16 v[84:87], v[166:169], v[4:7], v[84:87]
	v_mfma_f32_16x16x32_bf16 v[124:127], v[166:169], v[8:11], v[124:127]
	v_mfma_f32_16x16x32_bf16 v[144:147], v[166:169], v[12:15], v[144:147]
	s_waitcnt vmcnt(6)
	s_barrier
	v_add_u32_e32 v248, s30, v155
	v_add_u32_e32 v249, s30, v160
	v_mfma_f32_16x16x32_bf16 v[52:55], v[170:173], v[0:3], v[52:55]
	ds_read_b128 v[186:189], v248
	v_mfma_f32_16x16x32_bf16 v[36:39], v[170:173], v[4:7], v[36:39]
	ds_read_b128 v[212:215], v249 offset:8192
	v_mfma_f32_16x16x32_bf16 v[64:67], v[170:173], v[8:11], v[64:67]
	ds_read_b128 v[190:193], v248 offset:1024
	v_mfma_f32_16x16x32_bf16 v[76:79], v[170:173], v[12:15], v[76:79]
	ds_read_b128 v[216:219], v249 offset:9216
	v_mfma_f32_16x16x32_bf16 v[48:51], v[174:177], v[0:3], v[48:51]
	ds_read_b128 v[194:197], v248 offset:2048
	v_mfma_f32_16x16x32_bf16 v[32:35], v[174:177], v[4:7], v[32:35]
	ds_read_b128 v[220:223], v249 offset:10240
	v_mfma_f32_16x16x32_bf16 v[68:71], v[174:177], v[8:11], v[68:71]
	ds_read_b128 v[208:211], v248 offset:3072
	v_mfma_f32_16x16x32_bf16 v[72:75], v[174:177], v[12:15], v[72:75]
	ds_read_b128 v[224:227], v249 offset:11264
	v_mfma_f32_16x16x32_bf16 v[44:47], v[178:181], v[0:3], v[44:47]
	ds_read_b128 v[228:231], v249 offset:12288
	v_mfma_f32_16x16x32_bf16 v[28:31], v[178:181], v[4:7], v[28:31]
	ds_read_b128 v[232:235], v249 offset:13312
	v_mfma_f32_16x16x32_bf16 v[80:83], v[178:181], v[8:11], v[80:83]
	ds_read_b128 v[236:239], v249 offset:14336
	v_mfma_f32_16x16x32_bf16 v[60:63], v[178:181], v[12:15], v[60:63]
	ds_read_b128 v[240:243], v249 offset:15360
	v_mfma_f32_16x16x32_bf16 v[40:43], v[182:185], v[0:3], v[40:43]
	v_mfma_f32_16x16x32_bf16 v[24:27], v[182:185], v[4:7], v[24:27]
	v_mfma_f32_16x16x32_bf16 v[56:59], v[182:185], v[8:11], v[56:59]
	v_mfma_f32_16x16x32_bf16 v[148:151], v[182:185], v[12:15], v[148:151]
	s_add_u32 s30, s30, 24576
	s_cmp_eq_u32 s30, 73728
	s_cselect_b32 s30, 0, s30
	s_waitcnt lgkmcnt(0)
	v_mfma_f32_16x16x32_bf16 v[128:131], v[212:215], v[186:189], v[128:131]
	v_mfma_f32_16x16x32_bf16 v[96:99], v[212:215], v[190:193], v[96:99]
	v_mfma_f32_16x16x32_bf16 v[108:111], v[212:215], v[194:197], v[108:111]
	v_mfma_f32_16x16x32_bf16 v[132:135], v[212:215], v[208:211], v[132:135]
	v_mfma_f32_16x16x32_bf16 v[116:119], v[216:219], v[186:189], v[116:119]
	v_mfma_f32_16x16x32_bf16 v[92:95], v[216:219], v[190:193], v[92:95]
	v_mfma_f32_16x16x32_bf16 v[112:115], v[216:219], v[194:197], v[112:115]
	v_mfma_f32_16x16x32_bf16 v[136:139], v[216:219], v[208:211], v[136:139]
	v_mfma_f32_16x16x32_bf16 v[104:107], v[220:223], v[186:189], v[104:107]
	v_mfma_f32_16x16x32_bf16 v[88:91], v[220:223], v[190:193], v[88:91]
	v_mfma_f32_16x16x32_bf16 v[120:123], v[220:223], v[194:197], v[120:123]
	v_mfma_f32_16x16x32_bf16 v[140:143], v[220:223], v[208:211], v[140:143]
	v_mfma_f32_16x16x32_bf16 v[100:103], v[224:227], v[186:189], v[100:103]
	v_mfma_f32_16x16x32_bf16 v[84:87], v[224:227], v[190:193], v[84:87]
	v_mfma_f32_16x16x32_bf16 v[124:127], v[224:227], v[194:197], v[124:127]
	v_mfma_f32_16x16x32_bf16 v[144:147], v[224:227], v[208:211], v[144:147]
	s_waitcnt vmcnt(0)
	s_barrier
	v_add_u32_e32 v248, s30, v155
	v_add_u32_e32 v249, s30, v160
	v_mfma_f32_16x16x32_bf16 v[52:55], v[228:231], v[186:189], v[52:55]
	ds_read_b128 v[0:3], v248
	v_mfma_f32_16x16x32_bf16 v[36:39], v[228:231], v[190:193], v[36:39]
	ds_read_b128 v[16:19], v249 offset:8192
	v_mfma_f32_16x16x32_bf16 v[64:67], v[228:231], v[194:197], v[64:67]
	ds_read_b128 v[4:7], v248 offset:1024
	v_mfma_f32_16x16x32_bf16 v[76:79], v[228:231], v[208:211], v[76:79]
	ds_read_b128 v[20:23], v249 offset:9216
	v_mfma_f32_16x16x32_bf16 v[48:51], v[232:235], v[186:189], v[48:51]
	ds_read_b128 v[8:11], v248 offset:2048
	v_mfma_f32_16x16x32_bf16 v[32:35], v[232:235], v[190:193], v[32:35]
	ds_read_b128 v[162:165], v249 offset:10240
	v_mfma_f32_16x16x32_bf16 v[68:71], v[232:235], v[194:197], v[68:71]
	ds_read_b128 v[12:15], v248 offset:3072
	v_mfma_f32_16x16x32_bf16 v[72:75], v[232:235], v[208:211], v[72:75]
	ds_read_b128 v[166:169], v249 offset:11264
	v_mfma_f32_16x16x32_bf16 v[44:47], v[236:239], v[186:189], v[44:47]
	ds_read_b128 v[170:173], v249 offset:12288
	v_mfma_f32_16x16x32_bf16 v[28:31], v[236:239], v[190:193], v[28:31]
	ds_read_b128 v[174:177], v249 offset:13312
	v_mfma_f32_16x16x32_bf16 v[80:83], v[236:239], v[194:197], v[80:83]
	ds_read_b128 v[178:181], v249 offset:14336
	v_mfma_f32_16x16x32_bf16 v[60:63], v[236:239], v[208:211], v[60:63]
	ds_read_b128 v[182:185], v249 offset:15360
	v_mfma_f32_16x16x32_bf16 v[40:43], v[240:243], v[186:189], v[40:43]
	v_mfma_f32_16x16x32_bf16 v[24:27], v[240:243], v[190:193], v[24:27]
	v_mfma_f32_16x16x32_bf16 v[56:59], v[240:243], v[194:197], v[56:59]
	v_mfma_f32_16x16x32_bf16 v[148:151], v[240:243], v[208:211], v[148:151]
	s_add_u32 s30, s30, 24576
	s_cmp_eq_u32 s30, 73728
	s_cselect_b32 s30, 0, s30
	s_waitcnt lgkmcnt(0)
	v_mfma_f32_16x16x32_bf16 v[128:131], v[16:19], v[0:3], v[128:131]
	v_mfma_f32_16x16x32_bf16 v[96:99], v[16:19], v[4:7], v[96:99]
	v_mfma_f32_16x16x32_bf16 v[108:111], v[16:19], v[8:11], v[108:111]
	v_mfma_f32_16x16x32_bf16 v[132:135], v[16:19], v[12:15], v[132:135]
	v_mfma_f32_16x16x32_bf16 v[116:119], v[20:23], v[0:3], v[116:119]
	v_mfma_f32_16x16x32_bf16 v[92:95], v[20:23], v[4:7], v[92:95]
	v_mfma_f32_16x16x32_bf16 v[112:115], v[20:23], v[8:11], v[112:115]
	v_mfma_f32_16x16x32_bf16 v[136:139], v[20:23], v[12:15], v[136:139]
	v_mfma_f32_16x16x32_bf16 v[104:107], v[162:165], v[0:3], v[104:107]
	v_mfma_f32_16x16x32_bf16 v[88:91], v[162:165], v[4:7], v[88:91]
	v_mfma_f32_16x16x32_bf16 v[120:123], v[162:165], v[8:11], v[120:123]
	v_mfma_f32_16x16x32_bf16 v[140:143], v[162:165], v[12:15], v[140:143]
	v_mfma_f32_16x16x32_bf16 v[100:103], v[166:169], v[0:3], v[100:103]
	v_mfma_f32_16x16x32_bf16 v[84:87], v[166:169], v[4:7], v[84:87]
	v_mfma_f32_16x16x32_bf16 v[124:127], v[166:169], v[8:11], v[124:127]
	v_mfma_f32_16x16x32_bf16 v[144:147], v[166:169], v[12:15], v[144:147]
	v_mfma_f32_16x16x32_bf16 v[52:55], v[170:173], v[0:3], v[52:55]
	v_mfma_f32_16x16x32_bf16 v[36:39], v[170:173], v[4:7], v[36:39]
	v_mfma_f32_16x16x32_bf16 v[64:67], v[170:173], v[8:11], v[64:67]
	v_mfma_f32_16x16x32_bf16 v[76:79], v[170:173], v[12:15], v[76:79]
	v_mfma_f32_16x16x32_bf16 v[48:51], v[174:177], v[0:3], v[48:51]
	v_mfma_f32_16x16x32_bf16 v[32:35], v[174:177], v[4:7], v[32:35]
	v_mfma_f32_16x16x32_bf16 v[68:71], v[174:177], v[8:11], v[68:71]
	v_mfma_f32_16x16x32_bf16 v[72:75], v[174:177], v[12:15], v[72:75]
	v_mfma_f32_16x16x32_bf16 v[44:47], v[178:181], v[0:3], v[44:47]
	v_mfma_f32_16x16x32_bf16 v[28:31], v[178:181], v[4:7], v[28:31]
	v_mfma_f32_16x16x32_bf16 v[80:83], v[178:181], v[8:11], v[80:83]
	v_mfma_f32_16x16x32_bf16 v[60:63], v[178:181], v[12:15], v[60:63]
	v_mfma_f32_16x16x32_bf16 v[40:43], v[182:185], v[0:3], v[40:43]
	v_mfma_f32_16x16x32_bf16 v[24:27], v[182:185], v[4:7], v[24:27]
	v_mfma_f32_16x16x32_bf16 v[56:59], v[182:185], v[8:11], v[56:59]
	v_mfma_f32_16x16x32_bf16 v[148:151], v[182:185], v[12:15], v[148:151]
	s_add_i32 s12, s12, s6
	s_add_i32 s11, s11, s9
	s_add_i32 s10, s10, s6
	s_cmpk_gt_u32 s12, 0x1ff
	s_cselect_b32 s23, 1, 0
	v_mov_b32 v250, v198
	s_nop 0
	v_and_b32_e32 v251, 15, v250
	v_bfe_u32 v156, v250, 4, 2
	v_bfe_u32 v157, v250, 6, 1
	v_bfe_u32 v158, v250, 7, 1
	v_lshl_add_u32 v158, v158, 6, s14
	v_add_u32_e32 v158, v158, v251
	v_lshl_add_u32 v157, v157, 7, s13
	v_lshl_add_u32 v159, v156, 2, v157
	v_lshlrev_b32_e32 v230, 6, v158
	v_lshrrev_b32_e32 v228, 5, v157
	v_lshlrev_b32_e32 v228, 21, v228
	v_lshl_add_u32 v228, v158, 6, v228
	v_lshl_add_u32 v228, v156, 3, v228
	v_and_b32_e32 v161, 1, v156
	v_mul_u32_u24_e32 v161, 24, v161
	v_add_u32_e32 v229, v228, v161
	s_mov_b32 s30, s92
	s_mov_b32 s31, s93
	global_load_dwordx4 v[0:3], v230, s[94:95]
	global_load_dwordx4 v[4:7], v230, s[94:95] offset:16
	global_load_dwordx4 v[8:11], v230, s[94:95] offset:32
	global_load_dwordx4 v[12:15], v230, s[94:95] offset:48
	global_load_dwordx4 v[16:19], v230, s[94:95] offset:1024
	global_load_dwordx4 v[20:23], v230, s[94:95] offset:1040
	global_load_dwordx4 v[162:165], v230, s[94:95] offset:1056
	global_load_dwordx4 v[166:169], v230, s[94:95] offset:1072
	global_load_dwordx4 v[170:173], v230, s[94:95] offset:2048
	global_load_dwordx4 v[174:177], v230, s[94:95] offset:2064
	global_load_dwordx4 v[178:181], v230, s[94:95] offset:2080
	global_load_dwordx4 v[182:185], v230, s[94:95] offset:2096
	global_load_dwordx4 v[186:189], v230, s[94:95] offset:3072
	global_load_dwordx4 v[190:193], v230, s[94:95] offset:3088
	global_load_dwordx4 v[194:197], v230, s[94:95] offset:3104
	global_load_dwordx4 v[208:211], v230, s[94:95] offset:3120
	s_waitcnt vmcnt(12)
	v_add_f32_e32 v231, v0, v1
	v_add_f32_e32 v248, v2, v3
	v_add_f32_e32 v231, v231, v248
	v_add_f32_e32 v249, v4, v5
	v_add_f32_e32 v248, v6, v7
	v_add_f32_e32 v249, v249, v248
	v_add_f32_e32 v231, v231, v249
	v_add_f32_e32 v249, v8, v9
	v_add_f32_e32 v248, v10, v11
	v_add_f32_e32 v249, v249, v248
	v_add_f32_e32 v231, v231, v249
	v_add_f32_e32 v249, v12, v13
	v_add_f32_e32 v248, v14, v15
	v_add_f32_e32 v249, v249, v248
	v_add_f32_e32 v231, v231, v249
	v_fmamk_f32 v231, v231, 0x3a800000, v199
	v_cmp_gt_f32_e32 vcc, s73, v231
	v_mul_f32_e32 v248, 0x4b800000, v231
	s_nop 0
	v_cndmask_b32_e32 v231, v231, v248, vcc
	v_rsq_f32_e32 v231, v231
	s_nop 0
	v_mul_f32_e32 v248, 0x45800000, v231
	v_cndmask_b32_e32 v231, v231, v248, vcc
	v_mul_f32_e32 v212, v128, v231
	v_mul_f32_e32 v249, v129, v231
	v_mul_f32_e32 v213, v130, v231
	v_mul_f32_e32 v248, v131, v231
	v_max_f32_e32 v212, 0, v212
	v_max_f32_e32 v249, 0, v249
	v_max_f32_e32 v213, 0, v213
	v_max_f32_e32 v248, 0, v248
	v_mul_f32_e32 v212, v212, v212
	v_mul_f32_e32 v249, v249, v249
	v_mul_f32_e32 v213, v213, v213
	v_mul_f32_e32 v248, v248, v248
	v_cvt_pk_bf16_f32 v212, v212, v249
	v_cvt_pk_bf16_f32 v213, v213, v248
	v_mul_f32_e32 v214, v116, v231
	v_mul_f32_e32 v249, v117, v231
	v_mul_f32_e32 v215, v118, v231
	v_mul_f32_e32 v248, v119, v231
	v_max_f32_e32 v214, 0, v214
	v_max_f32_e32 v249, 0, v249
	v_max_f32_e32 v215, 0, v215
	v_max_f32_e32 v248, 0, v248
	v_mul_f32_e32 v214, v214, v214
	v_mul_f32_e32 v249, v249, v249
	v_mul_f32_e32 v215, v215, v215
	v_mul_f32_e32 v248, v248, v248
	v_cvt_pk_bf16_f32 v214, v214, v249
	v_cvt_pk_bf16_f32 v215, v215, v248
	s_add_u32 s30, s92, 0x0
	s_addc_u32 s31, s93, 0
	s_nop 0
	v_permlane16_swap_b32_e32 v212, v214
	v_permlane16_swap_b32_e32 v213, v215
	global_store_dwordx4 v229, v[212:215], s[30:31] nt
	v_mul_f32_e32 v216, v104, v231
	v_mul_f32_e32 v249, v105, v231
	v_mul_f32_e32 v217, v106, v231
	v_mul_f32_e32 v248, v107, v231
	v_max_f32_e32 v216, 0, v216
	v_max_f32_e32 v249, 0, v249
	v_max_f32_e32 v217, 0, v217
	v_max_f32_e32 v248, 0, v248
	v_mul_f32_e32 v216, v216, v216
	v_mul_f32_e32 v249, v249, v249
	v_mul_f32_e32 v217, v217, v217
	v_mul_f32_e32 v248, v248, v248
	v_cvt_pk_bf16_f32 v216, v216, v249
	v_cvt_pk_bf16_f32 v217, v217, v248
	v_mul_f32_e32 v218, v100, v231
	v_mul_f32_e32 v249, v101, v231
	v_mul_f32_e32 v219, v102, v231
	v_mul_f32_e32 v248, v103, v231
	v_max_f32_e32 v218, 0, v218
	v_max_f32_e32 v249, 0, v249
	v_max_f32_e32 v219, 0, v219
	v_max_f32_e32 v248, 0, v248
	v_mul_f32_e32 v218, v218, v218
	v_mul_f32_e32 v249, v249, v249
	v_mul_f32_e32 v219, v219, v219
	v_mul_f32_e32 v248, v248, v248
	v_cvt_pk_bf16_f32 v218, v218, v249
	v_cvt_pk_bf16_f32 v219, v219, v248
	s_add_u32 s30, s92, 0x200000
	s_addc_u32 s31, s93, 0
	s_nop 0
	v_permlane16_swap_b32_e32 v216, v218
	v_permlane16_swap_b32_e32 v217, v219
	global_store_dwordx4 v229, v[216:219], s[30:31] nt
	v_mul_f32_e32 v220, v52, v231
	v_mul_f32_e32 v249, v53, v231
	v_mul_f32_e32 v221, v54, v231
	v_mul_f32_e32 v248, v55, v231
	v_max_f32_e32 v220, 0, v220
	v_max_f32_e32 v249, 0, v249
	v_max_f32_e32 v221, 0, v221
	v_max_f32_e32 v248, 0, v248
	v_mul_f32_e32 v220, v220, v220
	v_mul_f32_e32 v249, v249, v249
	v_mul_f32_e32 v221, v221, v221
	v_mul_f32_e32 v248, v248, v248
	v_cvt_pk_bf16_f32 v220, v220, v249
	v_cvt_pk_bf16_f32 v221, v221, v248
	v_mul_f32_e32 v222, v48, v231
	v_mul_f32_e32 v249, v49, v231
	v_mul_f32_e32 v223, v50, v231
	v_mul_f32_e32 v248, v51, v231
	v_max_f32_e32 v222, 0, v222
	v_max_f32_e32 v249, 0, v249
	v_max_f32_e32 v223, 0, v223
	v_max_f32_e32 v248, 0, v248
	v_mul_f32_e32 v222, v222, v222
	v_mul_f32_e32 v249, v249, v249
	v_mul_f32_e32 v223, v223, v223
	v_mul_f32_e32 v248, v248, v248
	v_cvt_pk_bf16_f32 v222, v222, v249
	v_cvt_pk_bf16_f32 v223, v223, v248
	s_add_u32 s30, s92, 0x400000
	s_addc_u32 s31, s93, 0
	s_nop 0
	v_permlane16_swap_b32_e32 v220, v222
	v_permlane16_swap_b32_e32 v221, v223
	global_store_dwordx4 v229, v[220:223], s[30:31] nt
	v_mul_f32_e32 v224, v44, v231
	v_mul_f32_e32 v249, v45, v231
	v_mul_f32_e32 v225, v46, v231
	v_mul_f32_e32 v248, v47, v231
	v_max_f32_e32 v224, 0, v224
	v_max_f32_e32 v249, 0, v249
	v_max_f32_e32 v225, 0, v225
	v_max_f32_e32 v248, 0, v248
	v_mul_f32_e32 v224, v224, v224
	v_mul_f32_e32 v249, v249, v249
	v_mul_f32_e32 v225, v225, v225
	v_mul_f32_e32 v248, v248, v248
	v_cvt_pk_bf16_f32 v224, v224, v249
	v_cvt_pk_bf16_f32 v225, v225, v248
	v_mul_f32_e32 v226, v40, v231
	v_mul_f32_e32 v249, v41, v231
	v_mul_f32_e32 v227, v42, v231
	v_mul_f32_e32 v248, v43, v231
	v_max_f32_e32 v226, 0, v226
	v_max_f32_e32 v249, 0, v249
	v_max_f32_e32 v227, 0, v227
	v_max_f32_e32 v248, 0, v248
	v_mul_f32_e32 v226, v226, v226
	v_mul_f32_e32 v249, v249, v249
	v_mul_f32_e32 v227, v227, v227
	v_mul_f32_e32 v248, v248, v248
	v_cvt_pk_bf16_f32 v226, v226, v249
	v_cvt_pk_bf16_f32 v227, v227, v248
	s_add_u32 s30, s92, 0x600000
	s_addc_u32 s31, s93, 0
	s_nop 0
	v_permlane16_swap_b32_e32 v224, v226
	v_permlane16_swap_b32_e32 v225, v227
	global_store_dwordx4 v229, v[224:227], s[30:31] nt
	s_waitcnt vmcnt(12)
	v_add_f32_e32 v231, v16, v17
	v_add_f32_e32 v248, v18, v19
	v_add_f32_e32 v231, v231, v248
	v_add_f32_e32 v249, v20, v21
	v_add_f32_e32 v248, v22, v23
	v_add_f32_e32 v249, v249, v248
	v_add_f32_e32 v231, v231, v249
	v_add_f32_e32 v249, v162, v163
	v_add_f32_e32 v248, v164, v165
	v_add_f32_e32 v249, v249, v248
	v_add_f32_e32 v231, v231, v249
	v_add_f32_e32 v249, v166, v167
	v_add_f32_e32 v248, v168, v169
	v_add_f32_e32 v249, v249, v248
	v_add_f32_e32 v231, v231, v249
	v_fmamk_f32 v231, v231, 0x3a800000, v199
	v_cmp_gt_f32_e32 vcc, s73, v231
	v_mul_f32_e32 v248, 0x4b800000, v231
	s_nop 0
	v_cndmask_b32_e32 v231, v231, v248, vcc
	v_rsq_f32_e32 v231, v231
	s_nop 0
	v_mul_f32_e32 v248, 0x45800000, v231
	v_cndmask_b32_e32 v231, v231, v248, vcc
	v_mul_f32_e32 v212, v96, v231
	v_mul_f32_e32 v249, v97, v231
	v_mul_f32_e32 v213, v98, v231
	v_mul_f32_e32 v248, v99, v231
	v_max_f32_e32 v212, 0, v212
	v_max_f32_e32 v249, 0, v249
	v_max_f32_e32 v213, 0, v213
	v_max_f32_e32 v248, 0, v248
	v_mul_f32_e32 v212, v212, v212
	v_mul_f32_e32 v249, v249, v249
	v_mul_f32_e32 v213, v213, v213
	v_mul_f32_e32 v248, v248, v248
	v_cvt_pk_bf16_f32 v212, v212, v249
	v_cvt_pk_bf16_f32 v213, v213, v248
	v_mul_f32_e32 v214, v92, v231
	v_mul_f32_e32 v249, v93, v231
	v_mul_f32_e32 v215, v94, v231
	v_mul_f32_e32 v248, v95, v231
	v_max_f32_e32 v214, 0, v214
	v_max_f32_e32 v249, 0, v249
	v_max_f32_e32 v215, 0, v215
	v_max_f32_e32 v248, 0, v248
	v_mul_f32_e32 v214, v214, v214
	v_mul_f32_e32 v249, v249, v249
	v_mul_f32_e32 v215, v215, v215
	v_mul_f32_e32 v248, v248, v248
	v_cvt_pk_bf16_f32 v214, v214, v249
	v_cvt_pk_bf16_f32 v215, v215, v248
	s_add_u32 s30, s92, 0x400
	s_addc_u32 s31, s93, 0
	s_nop 0
	v_permlane16_swap_b32_e32 v212, v214
	v_permlane16_swap_b32_e32 v213, v215
	global_store_dwordx4 v229, v[212:215], s[30:31] nt
	v_mul_f32_e32 v216, v88, v231
	v_mul_f32_e32 v249, v89, v231
	v_mul_f32_e32 v217, v90, v231
	v_mul_f32_e32 v248, v91, v231
	v_max_f32_e32 v216, 0, v216
	v_max_f32_e32 v249, 0, v249
	v_max_f32_e32 v217, 0, v217
	v_max_f32_e32 v248, 0, v248
	v_mul_f32_e32 v216, v216, v216
	v_mul_f32_e32 v249, v249, v249
	v_mul_f32_e32 v217, v217, v217
	v_mul_f32_e32 v248, v248, v248
	v_cvt_pk_bf16_f32 v216, v216, v249
	v_cvt_pk_bf16_f32 v217, v217, v248
	v_mul_f32_e32 v218, v84, v231
	v_mul_f32_e32 v249, v85, v231
	v_mul_f32_e32 v219, v86, v231
	v_mul_f32_e32 v248, v87, v231
	v_max_f32_e32 v218, 0, v218
	v_max_f32_e32 v249, 0, v249
	v_max_f32_e32 v219, 0, v219
	v_max_f32_e32 v248, 0, v248
	v_mul_f32_e32 v218, v218, v218
	v_mul_f32_e32 v249, v249, v249
	v_mul_f32_e32 v219, v219, v219
	v_mul_f32_e32 v248, v248, v248
	v_cvt_pk_bf16_f32 v218, v218, v249
	v_cvt_pk_bf16_f32 v219, v219, v248
	s_add_u32 s30, s92, 0x200400
	s_addc_u32 s31, s93, 0
	s_nop 0
	v_permlane16_swap_b32_e32 v216, v218
	v_permlane16_swap_b32_e32 v217, v219
	global_store_dwordx4 v229, v[216:219], s[30:31] nt
	v_mul_f32_e32 v220, v36, v231
	v_mul_f32_e32 v249, v37, v231
	v_mul_f32_e32 v221, v38, v231
	v_mul_f32_e32 v248, v39, v231
	v_max_f32_e32 v220, 0, v220
	v_max_f32_e32 v249, 0, v249
	v_max_f32_e32 v221, 0, v221
	v_max_f32_e32 v248, 0, v248
	v_mul_f32_e32 v220, v220, v220
	v_mul_f32_e32 v249, v249, v249
	v_mul_f32_e32 v221, v221, v221
	v_mul_f32_e32 v248, v248, v248
	v_cvt_pk_bf16_f32 v220, v220, v249
	v_cvt_pk_bf16_f32 v221, v221, v248
	v_mul_f32_e32 v222, v32, v231
	v_mul_f32_e32 v249, v33, v231
	v_mul_f32_e32 v223, v34, v231
	v_mul_f32_e32 v248, v35, v231
	v_max_f32_e32 v222, 0, v222
	v_max_f32_e32 v249, 0, v249
	v_max_f32_e32 v223, 0, v223
	v_max_f32_e32 v248, 0, v248
	v_mul_f32_e32 v222, v222, v222
	v_mul_f32_e32 v249, v249, v249
	v_mul_f32_e32 v223, v223, v223
	v_mul_f32_e32 v248, v248, v248
	v_cvt_pk_bf16_f32 v222, v222, v249
	v_cvt_pk_bf16_f32 v223, v223, v248
	s_add_u32 s30, s92, 0x400400
	s_addc_u32 s31, s93, 0
	s_nop 0
	v_permlane16_swap_b32_e32 v220, v222
	v_permlane16_swap_b32_e32 v221, v223
	global_store_dwordx4 v229, v[220:223], s[30:31] nt
	v_mul_f32_e32 v224, v28, v231
	v_mul_f32_e32 v249, v29, v231
	v_mul_f32_e32 v225, v30, v231
	v_mul_f32_e32 v248, v31, v231
	v_max_f32_e32 v224, 0, v224
	v_max_f32_e32 v249, 0, v249
	v_max_f32_e32 v225, 0, v225
	v_max_f32_e32 v248, 0, v248
	v_mul_f32_e32 v224, v224, v224
	v_mul_f32_e32 v249, v249, v249
	v_mul_f32_e32 v225, v225, v225
	v_mul_f32_e32 v248, v248, v248
	v_cvt_pk_bf16_f32 v224, v224, v249
	v_cvt_pk_bf16_f32 v225, v225, v248
	v_mul_f32_e32 v226, v24, v231
	v_mul_f32_e32 v249, v25, v231
	v_mul_f32_e32 v227, v26, v231
	v_mul_f32_e32 v248, v27, v231
	v_max_f32_e32 v226, 0, v226
	v_max_f32_e32 v249, 0, v249
	v_max_f32_e32 v227, 0, v227
	v_max_f32_e32 v248, 0, v248
	v_mul_f32_e32 v226, v226, v226
	v_mul_f32_e32 v249, v249, v249
	v_mul_f32_e32 v227, v227, v227
	v_mul_f32_e32 v248, v248, v248
	v_cvt_pk_bf16_f32 v226, v226, v249
	v_cvt_pk_bf16_f32 v227, v227, v248
	s_add_u32 s30, s92, 0x600400
	s_addc_u32 s31, s93, 0
	s_nop 0
	v_permlane16_swap_b32_e32 v224, v226
	v_permlane16_swap_b32_e32 v225, v227
	global_store_dwordx4 v229, v[224:227], s[30:31] nt
	s_waitcnt vmcnt(12)
	v_add_f32_e32 v231, v170, v171
	v_add_f32_e32 v248, v172, v173
	v_add_f32_e32 v231, v231, v248
	v_add_f32_e32 v249, v174, v175
	v_add_f32_e32 v248, v176, v177
	v_add_f32_e32 v249, v249, v248
	v_add_f32_e32 v231, v231, v249
	v_add_f32_e32 v249, v178, v179
	v_add_f32_e32 v248, v180, v181
	v_add_f32_e32 v249, v249, v248
	v_add_f32_e32 v231, v231, v249
	v_add_f32_e32 v249, v182, v183
	v_add_f32_e32 v248, v184, v185
	v_add_f32_e32 v249, v249, v248
	v_add_f32_e32 v231, v231, v249
	v_fmamk_f32 v231, v231, 0x3a800000, v199
	v_cmp_gt_f32_e32 vcc, s73, v231
	v_mul_f32_e32 v248, 0x4b800000, v231
	s_nop 0
	v_cndmask_b32_e32 v231, v231, v248, vcc
	v_rsq_f32_e32 v231, v231
	s_nop 0
	v_mul_f32_e32 v248, 0x45800000, v231
	v_cndmask_b32_e32 v231, v231, v248, vcc
	v_mul_f32_e32 v212, v108, v231
	v_mul_f32_e32 v249, v109, v231
	v_mul_f32_e32 v213, v110, v231
	v_mul_f32_e32 v248, v111, v231
	v_max_f32_e32 v212, 0, v212
	v_max_f32_e32 v249, 0, v249
	v_max_f32_e32 v213, 0, v213
	v_max_f32_e32 v248, 0, v248
	v_mul_f32_e32 v212, v212, v212
	v_mul_f32_e32 v249, v249, v249
	v_mul_f32_e32 v213, v213, v213
	v_mul_f32_e32 v248, v248, v248
	v_cvt_pk_bf16_f32 v212, v212, v249
	v_cvt_pk_bf16_f32 v213, v213, v248
	v_mul_f32_e32 v214, v112, v231
	v_mul_f32_e32 v249, v113, v231
	v_mul_f32_e32 v215, v114, v231
	v_mul_f32_e32 v248, v115, v231
	v_max_f32_e32 v214, 0, v214
	v_max_f32_e32 v249, 0, v249
	v_max_f32_e32 v215, 0, v215
	v_max_f32_e32 v248, 0, v248
	v_mul_f32_e32 v214, v214, v214
	v_mul_f32_e32 v249, v249, v249
	v_mul_f32_e32 v215, v215, v215
	v_mul_f32_e32 v248, v248, v248
	v_cvt_pk_bf16_f32 v214, v214, v249
	v_cvt_pk_bf16_f32 v215, v215, v248
	s_add_u32 s30, s92, 0x800
	s_addc_u32 s31, s93, 0
	s_nop 0
	v_permlane16_swap_b32_e32 v212, v214
	v_permlane16_swap_b32_e32 v213, v215
	global_store_dwordx4 v229, v[212:215], s[30:31] nt
	v_mul_f32_e32 v216, v120, v231
	v_mul_f32_e32 v249, v121, v231
	v_mul_f32_e32 v217, v122, v231
	v_mul_f32_e32 v248, v123, v231
	v_max_f32_e32 v216, 0, v216
	v_max_f32_e32 v249, 0, v249
	v_max_f32_e32 v217, 0, v217
	v_max_f32_e32 v248, 0, v248
	v_mul_f32_e32 v216, v216, v216
	v_mul_f32_e32 v249, v249, v249
	v_mul_f32_e32 v217, v217, v217
	v_mul_f32_e32 v248, v248, v248
	v_cvt_pk_bf16_f32 v216, v216, v249
	v_cvt_pk_bf16_f32 v217, v217, v248
	v_mul_f32_e32 v218, v124, v231
	v_mul_f32_e32 v249, v125, v231
	v_mul_f32_e32 v219, v126, v231
	v_mul_f32_e32 v248, v127, v231
	v_max_f32_e32 v218, 0, v218
	v_max_f32_e32 v249, 0, v249
	v_max_f32_e32 v219, 0, v219
	v_max_f32_e32 v248, 0, v248
	v_mul_f32_e32 v218, v218, v218
	v_mul_f32_e32 v249, v249, v249
	v_mul_f32_e32 v219, v219, v219
	v_mul_f32_e32 v248, v248, v248
	v_cvt_pk_bf16_f32 v218, v218, v249
	v_cvt_pk_bf16_f32 v219, v219, v248
	s_add_u32 s30, s92, 0x200800
	s_addc_u32 s31, s93, 0
	s_nop 0
	v_permlane16_swap_b32_e32 v216, v218
	v_permlane16_swap_b32_e32 v217, v219
	global_store_dwordx4 v229, v[216:219], s[30:31] nt
	v_mul_f32_e32 v220, v64, v231
	v_mul_f32_e32 v249, v65, v231
	v_mul_f32_e32 v221, v66, v231
	v_mul_f32_e32 v248, v67, v231
	v_max_f32_e32 v220, 0, v220
	v_max_f32_e32 v249, 0, v249
	v_max_f32_e32 v221, 0, v221
	v_max_f32_e32 v248, 0, v248
	v_mul_f32_e32 v220, v220, v220
	v_mul_f32_e32 v249, v249, v249
	v_mul_f32_e32 v221, v221, v221
	v_mul_f32_e32 v248, v248, v248
	v_cvt_pk_bf16_f32 v220, v220, v249
	v_cvt_pk_bf16_f32 v221, v221, v248
	v_mul_f32_e32 v222, v68, v231
	v_mul_f32_e32 v249, v69, v231
	v_mul_f32_e32 v223, v70, v231
	v_mul_f32_e32 v248, v71, v231
	v_max_f32_e32 v222, 0, v222
	v_max_f32_e32 v249, 0, v249
	v_max_f32_e32 v223, 0, v223
	v_max_f32_e32 v248, 0, v248
	v_mul_f32_e32 v222, v222, v222
	v_mul_f32_e32 v249, v249, v249
	v_mul_f32_e32 v223, v223, v223
	v_mul_f32_e32 v248, v248, v248
	v_cvt_pk_bf16_f32 v222, v222, v249
	v_cvt_pk_bf16_f32 v223, v223, v248
	s_add_u32 s30, s92, 0x400800
	s_addc_u32 s31, s93, 0
	s_nop 0
	v_permlane16_swap_b32_e32 v220, v222
	v_permlane16_swap_b32_e32 v221, v223
	global_store_dwordx4 v229, v[220:223], s[30:31] nt
	v_mul_f32_e32 v224, v80, v231
	v_mul_f32_e32 v249, v81, v231
	v_mul_f32_e32 v225, v82, v231
	v_mul_f32_e32 v248, v83, v231
	v_max_f32_e32 v224, 0, v224
	v_max_f32_e32 v249, 0, v249
	v_max_f32_e32 v225, 0, v225
	v_max_f32_e32 v248, 0, v248
	v_mul_f32_e32 v224, v224, v224
	v_mul_f32_e32 v249, v249, v249
	v_mul_f32_e32 v225, v225, v225
	v_mul_f32_e32 v248, v248, v248
	v_cvt_pk_bf16_f32 v224, v224, v249
	v_cvt_pk_bf16_f32 v225, v225, v248
	v_mul_f32_e32 v226, v56, v231
	v_mul_f32_e32 v249, v57, v231
	v_mul_f32_e32 v227, v58, v231
	v_mul_f32_e32 v248, v59, v231
	v_max_f32_e32 v226, 0, v226
	v_max_f32_e32 v249, 0, v249
	v_max_f32_e32 v227, 0, v227
	v_max_f32_e32 v248, 0, v248
	v_mul_f32_e32 v226, v226, v226
	v_mul_f32_e32 v249, v249, v249
	v_mul_f32_e32 v227, v227, v227
	v_mul_f32_e32 v248, v248, v248
	v_cvt_pk_bf16_f32 v226, v226, v249
	v_cvt_pk_bf16_f32 v227, v227, v248
	s_add_u32 s30, s92, 0x600800
	s_addc_u32 s31, s93, 0
	s_nop 0
	v_permlane16_swap_b32_e32 v224, v226
	v_permlane16_swap_b32_e32 v225, v227
	global_store_dwordx4 v229, v[224:227], s[30:31] nt
	s_waitcnt vmcnt(12)
	v_add_f32_e32 v231, v186, v187
	v_add_f32_e32 v248, v188, v189
	v_add_f32_e32 v231, v231, v248
	v_add_f32_e32 v249, v190, v191
	v_add_f32_e32 v248, v192, v193
	v_add_f32_e32 v249, v249, v248
	v_add_f32_e32 v231, v231, v249
	v_add_f32_e32 v249, v194, v195
	v_add_f32_e32 v248, v196, v197
	v_add_f32_e32 v249, v249, v248
	v_add_f32_e32 v231, v231, v249
	v_add_f32_e32 v249, v208, v209
	v_add_f32_e32 v248, v210, v211
	v_add_f32_e32 v249, v249, v248
	v_add_f32_e32 v231, v231, v249
	v_fmamk_f32 v231, v231, 0x3a800000, v199
	v_cmp_gt_f32_e32 vcc, s73, v231
	v_mul_f32_e32 v248, 0x4b800000, v231
	s_nop 0
	v_cndmask_b32_e32 v231, v231, v248, vcc
	v_rsq_f32_e32 v231, v231
	s_nop 0
	v_mul_f32_e32 v248, 0x45800000, v231
	v_cndmask_b32_e32 v231, v231, v248, vcc
	v_mul_f32_e32 v212, v132, v231
	v_mul_f32_e32 v249, v133, v231
	v_mul_f32_e32 v213, v134, v231
	v_mul_f32_e32 v248, v135, v231
	v_max_f32_e32 v212, 0, v212
	v_max_f32_e32 v249, 0, v249
	v_max_f32_e32 v213, 0, v213
	v_max_f32_e32 v248, 0, v248
	v_mul_f32_e32 v212, v212, v212
	v_mul_f32_e32 v249, v249, v249
	v_mul_f32_e32 v213, v213, v213
	v_mul_f32_e32 v248, v248, v248
	v_cvt_pk_bf16_f32 v212, v212, v249
	v_cvt_pk_bf16_f32 v213, v213, v248
	v_mul_f32_e32 v214, v136, v231
	v_mul_f32_e32 v249, v137, v231
	v_mul_f32_e32 v215, v138, v231
	v_mul_f32_e32 v248, v139, v231
	v_max_f32_e32 v214, 0, v214
	v_max_f32_e32 v249, 0, v249
	v_max_f32_e32 v215, 0, v215
	v_max_f32_e32 v248, 0, v248
	v_mul_f32_e32 v214, v214, v214
	v_mul_f32_e32 v249, v249, v249
	v_mul_f32_e32 v215, v215, v215
	v_mul_f32_e32 v248, v248, v248
	v_cvt_pk_bf16_f32 v214, v214, v249
	v_cvt_pk_bf16_f32 v215, v215, v248
	s_add_u32 s30, s92, 0xc00
	s_addc_u32 s31, s93, 0
	s_nop 0
	v_permlane16_swap_b32_e32 v212, v214
	v_permlane16_swap_b32_e32 v213, v215
	global_store_dwordx4 v229, v[212:215], s[30:31] nt
	v_mul_f32_e32 v216, v140, v231
	v_mul_f32_e32 v249, v141, v231
	v_mul_f32_e32 v217, v142, v231
	v_mul_f32_e32 v248, v143, v231
	v_max_f32_e32 v216, 0, v216
	v_max_f32_e32 v249, 0, v249
	v_max_f32_e32 v217, 0, v217
	v_max_f32_e32 v248, 0, v248
	v_mul_f32_e32 v216, v216, v216
	v_mul_f32_e32 v249, v249, v249
	v_mul_f32_e32 v217, v217, v217
	v_mul_f32_e32 v248, v248, v248
	v_cvt_pk_bf16_f32 v216, v216, v249
	v_cvt_pk_bf16_f32 v217, v217, v248
	v_mul_f32_e32 v218, v144, v231
	v_mul_f32_e32 v249, v145, v231
	v_mul_f32_e32 v219, v146, v231
	v_mul_f32_e32 v248, v147, v231
	v_max_f32_e32 v218, 0, v218
	v_max_f32_e32 v249, 0, v249
	v_max_f32_e32 v219, 0, v219
	v_max_f32_e32 v248, 0, v248
	v_mul_f32_e32 v218, v218, v218
	v_mul_f32_e32 v249, v249, v249
	v_mul_f32_e32 v219, v219, v219
	v_mul_f32_e32 v248, v248, v248
	v_cvt_pk_bf16_f32 v218, v218, v249
	v_cvt_pk_bf16_f32 v219, v219, v248
	s_add_u32 s30, s92, 0x200c00
	s_addc_u32 s31, s93, 0
	s_nop 0
	v_permlane16_swap_b32_e32 v216, v218
	v_permlane16_swap_b32_e32 v217, v219
	global_store_dwordx4 v229, v[216:219], s[30:31] nt
	v_mul_f32_e32 v220, v76, v231
	v_mul_f32_e32 v249, v77, v231
	v_mul_f32_e32 v221, v78, v231
	v_mul_f32_e32 v248, v79, v231
	v_max_f32_e32 v220, 0, v220
	v_max_f32_e32 v249, 0, v249
	v_max_f32_e32 v221, 0, v221
	v_max_f32_e32 v248, 0, v248
	v_mul_f32_e32 v220, v220, v220
	v_mul_f32_e32 v249, v249, v249
	v_mul_f32_e32 v221, v221, v221
	v_mul_f32_e32 v248, v248, v248
	v_cvt_pk_bf16_f32 v220, v220, v249
	v_cvt_pk_bf16_f32 v221, v221, v248
	v_mul_f32_e32 v222, v72, v231
	v_mul_f32_e32 v249, v73, v231
	v_mul_f32_e32 v223, v74, v231
	v_mul_f32_e32 v248, v75, v231
	v_max_f32_e32 v222, 0, v222
	v_max_f32_e32 v249, 0, v249
	v_max_f32_e32 v223, 0, v223
	v_max_f32_e32 v248, 0, v248
	v_mul_f32_e32 v222, v222, v222
	v_mul_f32_e32 v249, v249, v249
	v_mul_f32_e32 v223, v223, v223
	v_mul_f32_e32 v248, v248, v248
	v_cvt_pk_bf16_f32 v222, v222, v249
	v_cvt_pk_bf16_f32 v223, v223, v248
	s_add_u32 s30, s92, 0x400c00
	s_addc_u32 s31, s93, 0
	s_nop 0
	v_permlane16_swap_b32_e32 v220, v222
	v_permlane16_swap_b32_e32 v221, v223
	global_store_dwordx4 v229, v[220:223], s[30:31] nt
	v_mul_f32_e32 v224, v60, v231
	v_mul_f32_e32 v249, v61, v231
	v_mul_f32_e32 v225, v62, v231
	v_mul_f32_e32 v248, v63, v231
	v_max_f32_e32 v224, 0, v224
	v_max_f32_e32 v249, 0, v249
	v_max_f32_e32 v225, 0, v225
	v_max_f32_e32 v248, 0, v248
	v_mul_f32_e32 v224, v224, v224
	v_mul_f32_e32 v249, v249, v249
	v_mul_f32_e32 v225, v225, v225
	v_mul_f32_e32 v248, v248, v248
	v_cvt_pk_bf16_f32 v224, v224, v249
	v_cvt_pk_bf16_f32 v225, v225, v248
	v_mul_f32_e32 v226, v148, v231
	v_mul_f32_e32 v249, v149, v231
	v_mul_f32_e32 v227, v150, v231
	v_mul_f32_e32 v248, v151, v231
	v_max_f32_e32 v226, 0, v226
	v_max_f32_e32 v249, 0, v249
	v_max_f32_e32 v227, 0, v227
	v_max_f32_e32 v248, 0, v248
	v_mul_f32_e32 v226, v226, v226
	v_mul_f32_e32 v249, v249, v249
	v_mul_f32_e32 v227, v227, v227
	v_mul_f32_e32 v248, v248, v248
	v_cvt_pk_bf16_f32 v226, v226, v249
	v_cvt_pk_bf16_f32 v227, v227, v248
	s_add_u32 s30, s92, 0x600c00
	s_addc_u32 s31, s93, 0
	s_nop 0
	v_permlane16_swap_b32_e32 v224, v226
	v_permlane16_swap_b32_e32 v225, v227
	global_store_dwordx4 v229, v[224:227], s[30:31] nt
	s_cmp_lg_u32 s23, 0
	s_cbranch_scc0 .LBB0_13
